# grid barrier grouped by the physical XCD (HW_REG_XCC_ID): only the last arriver of an XCD writes that L2 back (members' stores are already in it), per-XCD block counts taken at the first barrier
# speedup vs baseline: 1.0737x; 1.0145x over previous
; #define TIDX get_tid_()
; DI void phase0(const Params& p, char* lds) {
;   if (blockIdx.x == 0 && TIDX < 64) { ((unsigned*)(p.ws + OFF_MISC))[TIDX] = 0u; ((unsigned*)(p.ws + OFF_MISC + 6144))[TIDX] = 0u; }
;   for (int it = blockIdx.x; it < 4; it += gridDim.x) {
;     const int l = it >> 1, kv = it & 1;
;     const float* pe = p.in[kv ? I_PEV : I_PEK] + (size_t)l * 2048;
;     const float* w = p.in[kv ? I_PV1 : I_PK1] + (size_t)l * 2048 * 256;
;     const int n = TIDX;
;     if (n < 256) {
;       float s = 0.f;
;       for (int k = 0; k < 2048; ++k) s += pe[k] * w[(size_t)k * 256 + n];
;       ((float*)(p.ws + OFF_MISC + 256))[it * 256 + n] = s;
;     }
;   }
.LBB0_772:
	v_readlane_b32 s4, v254, 1
	v_readlane_b32 s24, v254, 46
	v_readlane_b32 s25, v254, 47
	v_lshrrev_b32_e32 v0, 6, v129
	s_nop 3
	s_cmp_gt_u32 s4, 15
	s_cbranch_scc1 .LBB0_773
	v_readlane_b32 s22, v253, 5
	v_readlane_b32 s23, v253, 6
	v_lshlrev_b32_e32 v2, 7, v129
	v_cmp_gt_u32_e32 vcc, 9, v129
	s_and_saveexec_b64 s[8:9], vcc
	s_nop 4
	global_store_dword v2, v131, s[22:23] offset:256
	global_store_dword v2, v131, s[22:23] offset:-1792
	v_lshlrev_b32_e32 v2, 2, v129
	global_store_dword v2, v131, s[22:23] offset:-768
	s_or_b64 exec, exec, s[8:9]
	v_readfirstlane_b32 s15, v0
	s_lshr_b32 s8, s4, 2
	s_and_b32 s26, s8, 1
	s_lshr_b32 s14, s8, 1
	s_lshl_b32 s9, s26, 3
	s_add_u32 s9, s9, 0x40
	s_load_dwordx2 s[22:23], s[24:25], s9
	s_lshl_b32 s9, s26, 4
	s_add_u32 s9, s9, 0x50
	s_load_dwordx2 s[10:11], s[24:25], s9
	s_lshl_b32 s54, s14, 13
	s_lshl_b32 s55, s15, 10
	s_add_u32 s54, s54, s55
	s_waitcnt lgkmcnt(0)
	s_add_u32 s22, s22, s54
	s_addc_u32 s23, s23, 0
	s_lshl_b32 s54, s14, 21
	s_lshl_b32 s55, s15, 18
	s_add_u32 s54, s54, s55
	s_and_b32 s55, s4, 3
	s_lshl_b32 s55, s55, 8
	s_add_u32 s54, s54, s55
	s_add_u32 s10, s10, s54
	s_addc_u32 s11, s11, 0
	v_and_b32_e32 v0, 63, v129
	v_lshlrev_b32_e32 v0, 2, v0
	v_mov_b32_e32 v1, 0
	s_mov_b32 s26, 8

; DI void grid_barrier(unsigned* ctr, unsigned target) {
;   __syncthreads();
;   if (threadIdx.x == 0) {
;     __threadfence();
;     __hip_atomic_fetch_add(ctr, 1u, __ATOMIC_RELAXED, __HIP_MEMORY_SCOPE_AGENT);
;     unsigned spins = 0;
;     while (__hip_atomic_load(ctr, __ATOMIC_RELAXED, __HIP_MEMORY_SCOPE_AGENT) < target && spins < (1u << 26)) { __builtin_amdgcn_s_sleep(2); ++spins; }
;     __threadfence();
;   }
;   __syncthreads();
; }
.LBB0_871:
	s_mov_b64 s[10:11], 0
	s_andn2_b64 vcc, exec, s[14:15]
	v_readlane_b32 s4, v254, 33
	s_cbranch_vccnz .LBB0_881
	v_readlane_b32 s4, v254, 33
	s_add_i32 s4, s4, 1
	s_waitcnt vmcnt(0) lgkmcnt(0)
	s_barrier
	s_mov_b64 s[8:9], exec
	v_readlane_b32 s10, v254, 36
	v_readlane_b32 s11, v254, 37
	s_and_b64 s[10:11], s[8:9], s[10:11]
	s_mov_b64 exec, s[10:11]
	s_cbranch_execz .LBB0_879
	v_readlane_b32 s24, v253, 5
	v_readlane_b32 s25, v253, 6
	v_mov_b32_e32 v0, 1
	s_cmp_eq_u32 s4, 1
	s_cbranch_scc0 .Lg3_real
	s_getreg_b32 s10, hwreg(HW_REG_XCC_ID, 0, 4)
	v_writelane_b32 v252, s10, 10
	s_lshl_b32 s10, s10, 2
	s_add_u32 s14, s24, s10
	s_addc_u32 s15, s25, 0
	buffer_wbl2 sc1
	global_atomic_add v131, v0, s[14:15] offset:-768
	v_readlane_b32 s10, v254, 1
	s_and_b32 s10, s10, 7
	s_sub_u32 s11, s33, s10
	s_add_u32 s11, s11, 7
	s_lshr_b32 s11, s11, 3
	s_lshl_b32 s10, s10, 7
	s_add_u32 s22, s24, s10
	s_addc_u32 s23, s25, 0
	s_waitcnt vmcnt(0)
	global_atomic_add v1, v131, v0, s[22:23] offset:256 sc0
	s_waitcnt vmcnt(0)
	v_add_u32_e32 v1, 1, v1
	v_cmp_eq_u32_e32 vcc, s11, v1
	s_mov_b32 s10, 0
	s_cbranch_vccz .Lg3_w1
	global_atomic_add v131, v0, s[24:25] offset:-1792
	global_atomic_add v131, v0, s[24:25] offset:-1664
	global_atomic_add v131, v0, s[24:25] offset:-1536
	global_atomic_add v131, v0, s[24:25] offset:-1408
	global_atomic_add v131, v0, s[24:25] offset:-1280
	global_atomic_add v131, v0, s[24:25] offset:-1152
	global_atomic_add v131, v0, s[24:25] offset:-1024
	global_atomic_add v131, v0, s[24:25] offset:-896

; DI void grid_barrier(unsigned* ctr, unsigned target) {
;   __syncthreads();
;   if (threadIdx.x == 0) {
;     __threadfence();
;     __hip_atomic_fetch_add(ctr, 1u, __ATOMIC_RELAXED, __HIP_MEMORY_SCOPE_AGENT);
;     unsigned spins = 0;
;     while (__hip_atomic_load(ctr, __ATOMIC_RELAXED, __HIP_MEMORY_SCOPE_AGENT) < target && spins < (1u << 26)) { __builtin_amdgcn_s_sleep(2); ++spins; }
;     __threadfence();
;   }
;   __syncthreads();
; }
.Lg3_lpa:
	global_load_dword v1, v131, s[22:23] offset:-1792 sc1
	s_add_u32 s10, s10, 1
	s_waitcnt vmcnt(0)
	v_cmp_gt_u32_e32 vcc, s11, v1
	s_cbranch_vccz .Lg3_oka
	s_cmp_lt_u32 s10, 0x100000
	s_cbranch_scc1 .Lg3_lpa
.Lg3_oka:
	s_mov_b64 exec, 0xff
	v_mbcnt_lo_u32_b32 v2, -1, 0
	v_lshlrev_b32_e32 v2, 2, v2
	s_nop 0
	global_load_dword v1, v2, s[24:25] offset:-768 sc1
	v_readlane_b32 s10, v252, 10
	s_waitcnt vmcnt(0)
	v_cmp_ne_u32_e32 vcc, 0, v1
	s_nop 3
	v_readlane_b32 s11, v1, s10
	s_bcnt1_i32_b64 s14, vcc
	s_mov_b64 exec, 1
	v_writelane_b32 v252, s11, 11
	v_writelane_b32 v252, s14, 12
	s_branch .Lg3_done
.Lg3_real:
	v_readlane_b32 s10, v252, 10
	v_readlane_b32 s11, v252, 11
	s_sub_u32 s14, s33, s10
	s_add_u32 s14, s14, 7
	s_lshr_b32 s14, s14, 3
	s_sub_u32 s15, s4, 1
	s_mul_i32 s11, s11, s15
	s_add_u32 s11, s11, s14
	s_lshl_b32 s10, s10, 7
	s_add_u32 s22, s24, s10
	s_addc_u32 s23, s25, 0
	global_atomic_add v1, v131, v0, s[22:23] offset:256 sc0
	s_waitcnt vmcnt(0)
	v_add_u32_e32 v1, 1, v1
	v_cmp_eq_u32_e32 vcc, s11, v1
	s_mov_b32 s10, 0
	s_cbranch_vccz .Lg3_w2
	buffer_wbl2 sc1
	s_waitcnt vmcnt(0)
	global_atomic_add v131, v0, s[24:25] offset:-1792
	global_atomic_add v131, v0, s[24:25] offset:-1664
	global_atomic_add v131, v0, s[24:25] offset:-1536
	global_atomic_add v131, v0, s[24:25] offset:-1408
	global_atomic_add v131, v0, s[24:25] offset:-1280
	global_atomic_add v131, v0, s[24:25] offset:-1152
	global_atomic_add v131, v0, s[24:25] offset:-1024
	global_atomic_add v131, v0, s[24:25] offset:-896
.Lg3_w2:
	v_readlane_b32 s11, v252, 12
	s_min_u32 s14, s33, 8
	s_mul_i32 s11, s11, s15
	s_add_u32 s11, s11, s14

; DI void grid_barrier(unsigned* ctr, unsigned target) {
;   __syncthreads();
;   if (threadIdx.x == 0) {
;     __threadfence();
;     __hip_atomic_fetch_add(ctr, 1u, __ATOMIC_RELAXED, __HIP_MEMORY_SCOPE_AGENT);
;     unsigned spins = 0;
;     while (__hip_atomic_load(ctr, __ATOMIC_RELAXED, __HIP_MEMORY_SCOPE_AGENT) < target && spins < (1u << 26)) { __builtin_amdgcn_s_sleep(2); ++spins; }
;     __threadfence();
;   }
;   __syncthreads();
; }
.Lg3_okb:
.Lg3_done:
	buffer_inv sc1
